# adds GLA scan software prefetch: next chunk's q~/attn/khT/e fragments loaded one step ahead into a second VGPR set (loop unrolled x2), on top of the attention loop rewrite
# speedup vs baseline: 1.0502x; 1.0018x over previous
; DI int opaque_bid() { int b = blockIdx.x; asm volatile("" : "+s"(b)); return b; }
; DI int opaque_gdim() { int g = gridDim.x; asm volatile("" : "+s"(g)); return g; }
; DI void phase_scan(int wid0, const Params& p, unsigned char* lds, bool dry) {
;     ...
;     for (int u = opaque_bid(); u < 256; u += opaque_gdim()) {
;         const int xcd = u & 7, ix = u >> 3, bh = xcd * 4 + (ix >> 3), vsi = ix & 7, b = bh >> 2, hd = bh & 3, colv = hd * 512 + vsi * 64;
;     ...
;         __syncthreads();
;     }
.LBB0_228:
	v_mov_b64_e32 v[164:165], 0x400
	v_mov_b64_e32 v[166:167], 0x3ff
	v_mov_b64_e32 v[168:169], 0xc00
	v_mov_b64_e32 v[170:171], 0xbff
	v_mov_b64_e32 v[172:173], 0x200
	v_mov_b64_e32 v[174:175], 0x1ff
	v_mov_b32_e32 v184, 0x3f4ccccd
	v_mov_b32_e32 v185, 0x358637bd
	v_mov_b32_e32 v186, 1
	v_mov_b32_e32 v187, 0x81
	v_mov_b32_e32 v232, v1
	v_mov_b32_e32 v233, v1
	v_mov_b32_e32 v234, v1
	v_mov_b32_e32 v235, v1
	s_mov_b32 s2, s20
	s_waitcnt lgkmcnt(0)
	s_barrier
	s_add_i32 s12, s2, s12
	s_cmpk_gt_i32 s12, 0xff
	s_cbranch_scc1 .LBB0_242

; DI void phase_scan(int wid0, const Params& p, unsigned char* lds, bool dry) {
;     ...
;         u32x4 vnext = *(const u32x4*)(vb + (size_t)(MREG + vj) * 2048 + colv + vc8);
;         for (int c = 0; c < 65; ++c) {
;             const int g = (c == 0) ? 512 : b * 64 + (c - 1), row0 = (c == 0) ? MREG : g * 64, ug = g * 4 + hd, cur = c & 1;
;             const int ib = wave >> 1, cb0 = 2 * (wave & 1), i = 16 * ib + l15;
;             bf16x8 at[2], aq[8], kt[4]; f32x4 evv[4];
;             {
;                 const bf16_t* ap = attn + (size_t)ug * 4096 + (ib * 2 * 64 + lane) * 8;
; #pragma unroll
;                 for (int s = 0; s < 2; ++s) at[s] = *(const bf16x8*)(ap + s * 512);
; #pragma unroll
;                 for (int s = 0; s < 8; ++s) { const int ob = ((ib * 8 + s) * 64 + lane) * 16; aq[s] = *(const bf16x8*)(qb + (size_t)(row0 + (ob >> 9)) * 1024 + hd * 256 + ((ob & 511) >> 1)); }
;                 const bf16_t* kp = khT + (size_t)ug * 16384 + (wave * 4 * 64 + lane) * 8;
; #pragma unroll
;                 for (int s = 0; s < 4; ++s) kt[s] = *(const bf16x8*)(kp + s * 512);
;                 const float* ep = Eo + (size_t)ug * 256 + 32 * wave + 4 * hi;
; #pragma unroll
;                 for (int g4 = 0; g4 < 4; ++g4) evv[g4] = *(const f32x4*)(ep + 8 * g4);
;             }
.LBB0_240:
	s_mov_b32 s84, s6
	s_mov_b32 s88, s8
	s_ashr_i32 s85, s84, 31
	s_lshl_b64 s[86:87], s[84:85], 13
	v_lshl_add_u64 v[196:197], v[132:133], 0, s[86:87]
	global_load_dwordx4 v[118:121], v[196:197], off
	global_load_dwordx4 v[122:125], v[196:197], off offset:1024
	v_add_u32_e32 v196, s88, v195
	v_add_u32_e32 v198, 0, v196
	v_ashrrev_i32_e32 v199, 31, v198
	v_lshlrev_b64 v[198:199], 11, v[198:199]
	v_lshl_add_u64 v[198:199], v[162:163], 0, v[198:199]
	global_load_dwordx4 v[114:117], v[198:199], off
	v_add_u32_e32 v198, 2, v196
	v_ashrrev_i32_e32 v199, 31, v198
	v_lshlrev_b64 v[198:199], 11, v[198:199]
	v_lshl_add_u64 v[198:199], v[162:163], 0, v[198:199]
	global_load_dwordx4 v[98:101], v[198:199], off
	v_add_u32_e32 v198, 4, v196
	v_ashrrev_i32_e32 v199, 31, v198
	v_lshlrev_b64 v[198:199], 11, v[198:199]
	v_lshl_add_u64 v[198:199], v[162:163], 0, v[198:199]
	global_load_dwordx4 v[110:113], v[198:199], off
	v_add_u32_e32 v198, 6, v196
	v_ashrrev_i32_e32 v199, 31, v198
	v_lshlrev_b64 v[198:199], 11, v[198:199]
	v_lshl_add_u64 v[198:199], v[162:163], 0, v[198:199]
	global_load_dwordx4 v[86:89], v[198:199], off
	v_add_u32_e32 v198, 8, v196
	v_ashrrev_i32_e32 v199, 31, v198
	v_lshlrev_b64 v[198:199], 11, v[198:199]
	v_lshl_add_u64 v[198:199], v[162:163], 0, v[198:199]
	global_load_dwordx4 v[102:105], v[198:199], off
	v_add_u32_e32 v198, 10, v196
	v_ashrrev_i32_e32 v199, 31, v198
	v_lshlrev_b64 v[198:199], 11, v[198:199]
	v_lshl_add_u64 v[198:199], v[162:163], 0, v[198:199]
	global_load_dwordx4 v[90:93], v[198:199], off
	v_add_u32_e32 v198, 12, v196
	v_ashrrev_i32_e32 v199, 31, v198
	v_lshlrev_b64 v[198:199], 11, v[198:199]
	v_lshl_add_u64 v[198:199], v[162:163], 0, v[198:199]
	global_load_dwordx4 v[106:109], v[198:199], off
	v_add_u32_e32 v198, 14, v196
	v_ashrrev_i32_e32 v199, 31, v198
	v_lshlrev_b64 v[198:199], 11, v[198:199]
	v_lshl_add_u64 v[198:199], v[162:163], 0, v[198:199]
	global_load_dwordx4 v[94:97], v[198:199], off
	s_lshl_b64 s[86:87], s[84:85], 15
	v_lshl_add_u64 v[200:201], v[136:137], 0, s[86:87]
	s_lshl_b64 s[86:87], s[84:85], 10
	v_lshl_add_u64 v[202:203], v[138:139], 0, s[86:87]
	global_load_dwordx4 v[50:53], v[200:201], off
	global_load_dwordx4 v[46:49], v[200:201], off offset:1024
	global_load_dwordx4 v[42:45], v[200:201], off offset:2048
	global_load_dwordx4 v[38:41], v[200:201], off offset:3072
	global_load_dwordx4 v[66:69], v[202:203], off
	global_load_dwordx4 v[54:57], v[202:203], off offset:32
	global_load_dwordx4 v[58:61], v[202:203], off offset:64
	global_load_dwordx4 v[70:73], v[202:203], off offset:96
.Lscan_top_A:
	s_cmpk_eq_i32 s8, 0xfc0
	s_cbranch_scc1 .Lscan_last_A
	s_add_i32 s84, s6, 4
	s_add_i32 s88, s8, 64
	s_ashr_i32 s85, s84, 31
	s_lshl_b64 s[86:87], s[84:85], 13
	v_lshl_add_u64 v[196:197], v[132:133], 0, s[86:87]
	global_load_dwordx4 v[214:217], v[196:197], off
	global_load_dwordx4 v[218:221], v[196:197], off offset:1024
	v_add_u32_e32 v196, s88, v195
	v_add_u32_e32 v198, 0, v196
	v_ashrrev_i32_e32 v199, 31, v198
	v_lshlrev_b64 v[198:199], 11, v[198:199]
	v_lshl_add_u64 v[198:199], v[162:163], 0, v[198:199]
	global_load_dwordx4 v[222:225], v[198:199], off
	v_add_u32_e32 v198, 2, v196
	v_ashrrev_i32_e32 v199, 31, v198
	v_lshlrev_b64 v[198:199], 11, v[198:199]
	v_lshl_add_u64 v[198:199], v[162:163], 0, v[198:199]
	global_load_dwordx4 v[226:229], v[198:199], off
	v_add_u32_e32 v198, 4, v196
	v_ashrrev_i32_e32 v199, 31, v198
	v_lshlrev_b64 v[198:199], 11, v[198:199]
	v_lshl_add_u64 v[198:199], v[162:163], 0, v[198:199]
	global_load_dwordx4 v[236:239], v[198:199], off
	v_add_u32_e32 v198, 6, v196
	v_ashrrev_i32_e32 v199, 31, v198
	v_lshlrev_b64 v[198:199], 11, v[198:199]
	v_lshl_add_u64 v[198:199], v[162:163], 0, v[198:199]
	global_load_dwordx4 v[240:243], v[198:199], off
	v_add_u32_e32 v198, 8, v196
	v_ashrrev_i32_e32 v199, 31, v198
	v_lshlrev_b64 v[198:199], 11, v[198:199]
	v_lshl_add_u64 v[198:199], v[162:163], 0, v[198:199]
	global_load_dwordx4 v[248:251], v[198:199], off
	v_add_u32_e32 v198, 10, v196
	v_ashrrev_i32_e32 v199, 31, v198
	v_lshlrev_b64 v[198:199], 11, v[198:199]
	v_lshl_add_u64 v[198:199], v[162:163], 0, v[198:199]
	global_load_dwordx4 v[252:255], v[198:199], off
	v_add_u32_e32 v198, 12, v196
	v_ashrrev_i32_e32 v199, 31, v198
	v_lshlrev_b64 v[198:199], 11, v[198:199]
	v_lshl_add_u64 v[198:199], v[162:163], 0, v[198:199]
	global_load_dwordx4 v[140:143], v[198:199], off
	v_add_u32_e32 v198, 14, v196
	v_ashrrev_i32_e32 v199, 31, v198
	v_lshlrev_b64 v[198:199], 11, v[198:199]
	v_lshl_add_u64 v[198:199], v[162:163], 0, v[198:199]
	global_load_dwordx4 v[146:149], v[198:199], off
	s_lshl_b64 s[86:87], s[84:85], 15
	v_lshl_add_u64 v[200:201], v[136:137], 0, s[86:87]
	s_lshl_b64 s[86:87], s[84:85], 10
	v_lshl_add_u64 v[202:203], v[138:139], 0, s[86:87]
	global_load_dwordx4 v[150:153], v[200:201], off
	global_load_dwordx4 v[154:157], v[200:201], off offset:1024
	global_load_dwordx4 v[158:161], v[200:201], off offset:2048
	global_load_dwordx4 v[164:167], v[200:201], off offset:3072
	global_load_dwordx4 v[168:171], v[202:203], off
	global_load_dwordx4 v[172:175], v[202:203], off offset:32
	global_load_dwordx4 v[184:187], v[202:203], off offset:64
	global_load_dwordx4 v[232:235], v[202:203], off offset:96
	s_cmp_eq_u32 s8, 0
	s_cbranch_scc1 .Lscan_first_A
	s_waitcnt vmcnt(20)
	s_branch .Lscan_go_A
.Lscan_first_A:
	s_waitcnt vmcnt(18)
	s_branch .Lscan_go_A

; #define MFMA16(a, b, c) __builtin_amdgcn_mfma_f32_16x16x32_bf16((a), (b), (c), 0, 0, 0)
; DI void phase_scan(int wid0, const Params& p, unsigned char* lds, bool dry) {
;     ...
;             *(u32x4*)(vs + cur * 4608 + vj * 72 + vc8) = vnext;
;             LDS_BARRIER();
;             if (c + 1 < 65) vnext = *(const u32x4*)(vb + (size_t)((b * 64 + c) * 64 + vj) * 2048 + colv + vc8);
;             const unsigned vao = vs_base + (unsigned)(cur * 9216 + (8 * l4 + (l15 >> 2)) * 144 + 2 * (16 * cb0 + 4 * (l15 & 3)));
;             const unsigned vau = vs_base + (unsigned)(cur * 9216 + (8 * hi + (l15 >> 2)) * 144 + 2 * (16 * ((lane >> 4) & 1) + 4 * (l15 & 3)));
;             s16x4 ol[2][2], oh[2][2], ul0[4], uh0[4], ul1[4], uh1[4];
; #pragma unroll
;             for (int cc = 0; cc < 2; ++cc)
; #pragma unroll
;                 for (int s = 0; s < 2; ++s) { ol[cc][s] = tr_read0(vao + cc * 32 + s * 32 * 144); oh[cc][s] = tr_read0(vao + cc * 32 + s * 32 * 144 + 4 * 144); }
; #pragma unroll
;             for (int s = 0; s < 2; ++s) {
;                 ul0[s] = tr_read0(vau + s * 16 * 144); uh0[s] = tr_read0(vau + s * 16 * 144 + 4 * 144);
;                 ul1[s] = tr_read0(vau + s * 16 * 144 + 64); uh1[s] = tr_read0(vau + s * 16 * 144 + 4 * 144 + 64);
;             }
;             {
;                 __builtin_amdgcn_sched_barrier(0);
;                 f32x4 oacc[2];
; #pragma unroll
;                 for (int cc = 0; cc < 2; ++cc) {
;                     const int cb = cb0 + cc; oacc[cc] = (f32x4){0.f, 0.f, 0.f, 0.f};
; #pragma unroll
;                     for (int s = 0; s < 2; ++s) oacc[cc] = MFMA16(PK8(ol[cc][s], oh[cc][s]), at[s], oacc[cc]);
;                     const bf16_t* sp = sbt + cur * 16896 + (16 * cb + l15) * 264 + 8 * l4;
; #pragma unroll
;                     for (int s = 0; s < 8; ++s) { const bf16x8 bfr = *(const bf16x8*)(sp + 32 * s); oacc[cc] = MFMA16(bfr, aq[s], oacc[cc]); }
;                 }
; #pragma unroll
;                 for (int s = 2; s < 4; ++s) {
;                     ul0[s] = tr_read0(vau + s * 16 * 144); uh0[s] = tr_read0(vau + s * 16 * 144 + 4 * 144);
;                     ul1[s] = tr_read0(vau + s * 16 * 144 + 64); uh1[s] = tr_read0(vau + s * 16 * 144 + 4 * 144 + 64);
;                 }
; #pragma unroll
;                 for (int cc = 0; cc < 2; ++cc) {
;                     const int col = colv + 16 * (cb0 + cc) + 4 * l4;
.Lscan_go_A:
	s_and_b32 s7, s2, 1
	s_mul_i32 s9, s7, 0x2400
	v_add_u32_e32 v62, s9, v127
	ds_write_b128 v62, v[34:37]
	s_waitcnt lgkmcnt(0)
	s_barrier
	s_cmpk_eq_i32 s8, 0xfc0
	s_cbranch_scc1 .Lscan_body_A
	v_add_u32_e32 v34, s8, v193
	v_ashrrev_i32_e32 v35, 31, v34
	v_lshlrev_b64 v[34:35], 12, v[34:35]
	v_lshl_add_u64 v[34:35], v[176:177], 0, v[34:35]
	global_load_dwordx4 v[34:37], v[34:35], off
.Lscan_body_A:
	v_add_u32_e32 v62, s9, v181
	v_add_u32_e32 v179, s9, v180
	ds_read_b64_tr_b16 v[198:199], v62 offset:576
	ds_read_b64_tr_b16 v[196:197], v62
	ds_read_b64_tr_b16 v[202:203], v62 offset:608
	ds_read_b64_tr_b16 v[200:201], v62 offset:32
	ds_read_b64_tr_b16 v[204:205], v62 offset:4608
	ds_read_b64_tr_b16 v[206:207], v62 offset:5184
	ds_read_b64_tr_b16 v[210:211], v62 offset:5216
	ds_read_b64_tr_b16 v[208:209], v62 offset:4640
	ds_read_b64_tr_b16 v[82:83], v179
	ds_read_b64_tr_b16 v[84:85], v179 offset:576
	ds_read_b64_tr_b16 v[80:81], v179 offset:640
	ds_read_b64_tr_b16 v[78:79], v179 offset:64
	ds_read_b64_tr_b16 v[74:75], v179 offset:2304
	ds_read_b64_tr_b16 v[76:77], v179 offset:2880
	ds_read_b64_tr_b16 v[64:65], v179 offset:2944
	ds_read_b64_tr_b16 v[62:63], v179 offset:2368
	s_waitcnt lgkmcnt(14)
	v_mfma_f32_16x16x32_bf16 v[196:199], v[196:199], v[118:121], 0
	s_mul_i32 s9, s7, 0x8400
	v_add_u32_e32 v212, s9, v182
	v_add_u32_e32 v213, v212, v145
	s_waitcnt lgkmcnt(12)
	v_mfma_f32_16x16x32_bf16 v[118:121], v[200:203], v[118:121], 0
	v_add_u32_e32 v200, v212, v189
	v_pk_mul_f32 v[32:33], v[32:33], v[72:73]
	v_pk_mul_f32 v[28:29], v[28:29], v[60:61]
	s_waitcnt lgkmcnt(10)
	v_mfma_f32_16x16x32_bf16 v[196:199], v[204:207], v[122:125], v[196:199]
	ds_read_b128 v[204:207], v213
	v_pk_mul_f32 v[24:25], v[24:25], v[56:57]
	v_pk_mul_f32 v[20:21], v[20:21], v[68:69]
	s_waitcnt lgkmcnt(9)
	v_mfma_f32_16x16x32_bf16 v[118:121], v[208:211], v[122:125], v[118:121]
	ds_read_b128 v[122:125], v200
	v_pk_mul_f32 v[18:19], v[18:19], v[66:67]
	v_pk_mul_f32 v[30:31], v[30:31], v[70:71]
	s_waitcnt lgkmcnt(1)
	v_mfma_f32_16x16x32_bf16 v[196:199], v[204:207], v[114:117], v[196:199]
	ds_read_b128 v[204:207], v213 offset:64
	v_pk_mul_f32 v[26:27], v[26:27], v[58:59]
	v_pk_mul_f32 v[22:23], v[22:23], v[54:55]
	s_waitcnt lgkmcnt(1)
	v_mfma_f32_16x16x32_bf16 v[114:117], v[122:125], v[114:117], v[118:121]
	v_mul_f32_e64 v16, v16, v72
	v_mul_f32_e64 v17, v17, v73
	v_pk_mul_f32 v[12:13], v[12:13], v[60:61]
	v_pk_mul_f32 v[8:9], v[8:9], v[56:57]
	ds_read_b128 v[118:121], v200 offset:64
	s_waitcnt lgkmcnt(1)
	v_mfma_f32_16x16x32_bf16 v[196:199], v[204:207], v[98:101], v[196:199]
	ds_read_b128 v[204:207], v213 offset:128
	v_pk_mul_f32 v[4:5], v[4:5], v[68:69]
	v_pk_mul_f32 v[2:3], v[2:3], v[66:67]
	s_waitcnt lgkmcnt(1)
	v_mfma_f32_16x16x32_bf16 v[98:101], v[118:121], v[98:101], v[114:117]
	s_nop 2
	ds_read_b128 v[114:117], v200 offset:128
	v_pk_mul_f32 v[14:15], v[14:15], v[70:71]
	v_pk_mul_f32 v[10:11], v[10:11], v[58:59]
	s_waitcnt lgkmcnt(1)
	v_mfma_f32_16x16x32_bf16 v[196:199], v[204:207], v[110:113], v[196:199]
	ds_read_b128 v[204:207], v213 offset:192
	v_pk_mul_f32 v[6:7], v[6:7], v[54:55]
	s_waitcnt lgkmcnt(1)
	v_mfma_f32_16x16x32_bf16 v[98:101], v[114:117], v[110:113], v[98:101]
	ds_read_b128 v[110:113], v200 offset:192
	s_waitcnt lgkmcnt(1)
	v_mfma_f32_16x16x32_bf16 v[196:199], v[204:207], v[86:89], v[196:199]
	ds_read_b128 v[204:207], v213 offset:256
	s_waitcnt lgkmcnt(1)
	v_mfma_f32_16x16x32_bf16 v[86:89], v[110:113], v[86:89], v[98:101]
	s_nop 2
	ds_read_b128 v[98:101], v200 offset:256
	s_waitcnt lgkmcnt(1)
	v_mfma_f32_16x16x32_bf16 v[196:199], v[204:207], v[102:105], v[196:199]
	ds_read_b128 v[204:207], v213 offset:320
	s_waitcnt lgkmcnt(1)
	v_mfma_f32_16x16x32_bf16 v[86:89], v[98:101], v[102:105], v[86:89]
	ds_read_b128 v[98:101], v200 offset:320
	s_waitcnt lgkmcnt(1)
	v_mfma_f32_16x16x32_bf16 v[196:199], v[204:207], v[90:93], v[196:199]
	ds_read_b128 v[204:207], v213 offset:384
	s_waitcnt lgkmcnt(1)
	v_mfma_f32_16x16x32_bf16 v[86:89], v[98:101], v[90:93], v[86:89]
	ds_read_b128 v[90:93], v200 offset:384
	s_waitcnt lgkmcnt(1)
	v_mfma_f32_16x16x32_bf16 v[196:199], v[204:207], v[106:109], v[196:199]
	ds_read_b128 v[204:207], v213 offset:448
	s_waitcnt lgkmcnt(1)
	v_mfma_f32_16x16x32_bf16 v[86:89], v[90:93], v[106:109], v[86:89]
	ds_read_b128 v[90:93], v200 offset:448
	v_add_u32_e32 v106, s8, v194
	v_ashrrev_i32_e32 v107, 31, v106
	s_waitcnt lgkmcnt(1)
	v_mfma_f32_16x16x32_bf16 v[196:199], v[204:207], v[94:97], v[196:199]
	v_lshlrev_b64 v[106:107], 12, v[106:107]
	v_lshl_add_u64 v[106:107], s[28:29], 0, v[106:107]
	v_lshl_add_u64 v[110:111], v[106:107], 0, v[0:1]
	s_waitcnt lgkmcnt(0)
	v_mfma_f32_16x16x32_bf16 v[86:89], v[90:93], v[94:97], v[86:89]
	ds_read_b64_tr_b16 v[90:91], v179 offset:4608
	ds_read_b64_tr_b16 v[92:93], v179 offset:5184
	ds_read_b64_tr_b16 v[94:95], v179 offset:4672
	ds_read_b64_tr_b16 v[96:97], v179 offset:5248
	ds_read_b64_tr_b16 v[98:99], v179 offset:6912
	ds_read_b64_tr_b16 v[100:101], v179 offset:7488
	ds_read_b64_tr_b16 v[102:103], v179 offset:6976
	ds_read_b64_tr_b16 v[104:105], v179 offset:7552
	v_mov_b32_e32 v179, v1
	v_cvt_pk_bf16_f32 v108, v196, v197
	v_cvt_pk_bf16_f32 v109, v198, v199
	v_cvt_pk_bf16_f32 v86, v86, v87
	v_cvt_pk_bf16_f32 v87, v88, v89
	v_lshl_add_u64 v[88:89], v[106:107], 0, v[178:179]
	global_store_dwordx2 v[110:111], v[108:109], off
	global_store_dwordx2 v[88:89], v[86:87], off
	v_mfma_f32_32x32x16_bf16 v[18:33], v[50:53], v[82:85], v[18:33]
	s_xor_b32 s7, s7, 1
	s_mul_i32 s7, s7, 0x8400
	s_add_i32 s8, s8, 64
	s_add_i32 s6, s6, 4
	s_add_i32 s2, s2, 1
	s_cmpk_eq_i32 s8, 0x1000
	v_mfma_f32_32x32x16_bf16 v[2:17], v[50:53], v[78:81], v[2:17]
	v_mfma_f32_32x32x16_bf16 v[18:33], v[46:49], v[74:77], v[18:33]
	v_mfma_f32_32x32x16_bf16 v[2:17], v[46:49], v[62:65], v[2:17]
	v_add_u32_e32 v46, s7, v131
	v_add_u32_e32 v47, 0x4000, v46
	s_waitcnt lgkmcnt(6)
	v_mfma_f32_32x32x16_bf16 v[18:33], v[42:45], v[90:93], v[18:33]
	s_waitcnt lgkmcnt(4)
	v_mfma_f32_32x32x16_bf16 v[2:17], v[42:45], v[94:97], v[2:17]
	s_waitcnt lgkmcnt(2)
	v_mfma_f32_32x32x16_bf16 v[18:33], v[38:41], v[98:101], v[18:33]
	s_waitcnt lgkmcnt(0)
	v_mfma_f32_32x32x16_bf16 v[2:17], v[38:41], v[102:105], v[2:17]
	s_nop 9
	v_cvt_pk_bf16_f32 v42, v18, v19
	v_cvt_pk_bf16_f32 v43, v20, v21
	v_cvt_pk_bf16_f32 v40, v22, v23
	v_cvt_pk_bf16_f32 v41, v24, v25
	ds_write2_b64 v46, v[42:43], v[40:41] offset1:2
	v_cvt_pk_bf16_f32 v42, v30, v31
	v_cvt_pk_bf16_f32 v43, v32, v33
	v_cvt_pk_bf16_f32 v38, v2, v3
	v_cvt_pk_bf16_f32 v39, v4, v5
	v_cvt_pk_bf16_f32 v44, v6, v7
	v_cvt_pk_bf16_f32 v45, v8, v9
	ds_write2_b64 v47, v[38:39], v[44:45] offset0:64 offset1:66
	v_cvt_pk_bf16_f32 v38, v26, v27
	v_cvt_pk_bf16_f32 v39, v28, v29
	v_cvt_pk_bf16_f32 v40, v10, v11
	v_cvt_pk_bf16_f32 v41, v12, v13
	v_cvt_pk_bf16_f32 v44, v14, v15
	v_cvt_pk_bf16_f32 v45, v16, v17
	ds_write2_b64 v46, v[38:39], v[42:43] offset0:4 offset1:6
	ds_write2_b64 v47, v[40:41], v[44:45] offset0:68 offset1:70
	s_cbranch_scc1 .LBB0_228
; DI void phase_scan(int wid0, const Params& p, unsigned char* lds, bool dry) {
;     ...
;             const int g = (c == 0) ? 512 : b * 64 + (c - 1), row0 = (c == 0) ? MREG : g * 64, ug = g * 4 + hd, cur = c & 1;
;             const int ib = wave >> 1, cb0 = 2 * (wave & 1), i = 16 * ib + l15;
;             bf16x8 at[2], aq[8], kt[4]; f32x4 evv[4];
;             {
;                 const bf16_t* ap = attn + (size_t)ug * 4096 + (ib * 2 * 64 + lane) * 8;
; #pragma unroll
;                 for (int s = 0; s < 2; ++s) at[s] = *(const bf16x8*)(ap + s * 512);
; #pragma unroll
;                 for (int s = 0; s < 8; ++s) { const int ob = ((ib * 8 + s) * 64 + lane) * 16; aq[s] = *(const bf16x8*)(qb + (size_t)(row0 + (ob >> 9)) * 1024 + hd * 256 + ((ob & 511) >> 1)); }
;                 const bf16_t* kp = khT + (size_t)ug * 16384 + (wave * 4 * 64 + lane) * 8;
; #pragma unroll
;                 for (int s = 0; s < 4; ++s) kt[s] = *(const bf16x8*)(kp + s * 512);
;                 const float* ep = Eo + (size_t)ug * 256 + 32 * wave + 4 * hi;
; #pragma unroll
;                 for (int g4 = 0; g4 < 4; ++g4) evv[g4] = *(const f32x4*)(ep + 8 * g4);
;             }
.Lscan_top_B:
	s_cmpk_eq_i32 s8, 0xfc0
	s_cbranch_scc1 .Lscan_last_B
	s_add_i32 s84, s6, 4
	s_add_i32 s88, s8, 64
	s_ashr_i32 s85, s84, 31
	s_lshl_b64 s[86:87], s[84:85], 13
	v_lshl_add_u64 v[196:197], v[132:133], 0, s[86:87]
	global_load_dwordx4 v[118:121], v[196:197], off
	global_load_dwordx4 v[122:125], v[196:197], off offset:1024
	v_add_u32_e32 v196, s88, v195
	v_add_u32_e32 v198, 0, v196
	v_ashrrev_i32_e32 v199, 31, v198
	v_lshlrev_b64 v[198:199], 11, v[198:199]
	v_lshl_add_u64 v[198:199], v[162:163], 0, v[198:199]
	global_load_dwordx4 v[114:117], v[198:199], off
	v_add_u32_e32 v198, 2, v196
	v_ashrrev_i32_e32 v199, 31, v198
	v_lshlrev_b64 v[198:199], 11, v[198:199]
	v_lshl_add_u64 v[198:199], v[162:163], 0, v[198:199]
	global_load_dwordx4 v[98:101], v[198:199], off
	v_add_u32_e32 v198, 4, v196
	v_ashrrev_i32_e32 v199, 31, v198
	v_lshlrev_b64 v[198:199], 11, v[198:199]
	v_lshl_add_u64 v[198:199], v[162:163], 0, v[198:199]
	global_load_dwordx4 v[110:113], v[198:199], off
	v_add_u32_e32 v198, 6, v196
	v_ashrrev_i32_e32 v199, 31, v198
	v_lshlrev_b64 v[198:199], 11, v[198:199]
	v_lshl_add_u64 v[198:199], v[162:163], 0, v[198:199]
	global_load_dwordx4 v[86:89], v[198:199], off
	v_add_u32_e32 v198, 8, v196
	v_ashrrev_i32_e32 v199, 31, v198
	v_lshlrev_b64 v[198:199], 11, v[198:199]
	v_lshl_add_u64 v[198:199], v[162:163], 0, v[198:199]
	global_load_dwordx4 v[102:105], v[198:199], off
	v_add_u32_e32 v198, 10, v196
	v_ashrrev_i32_e32 v199, 31, v198
	v_lshlrev_b64 v[198:199], 11, v[198:199]
	v_lshl_add_u64 v[198:199], v[162:163], 0, v[198:199]
	global_load_dwordx4 v[90:93], v[198:199], off
	v_add_u32_e32 v198, 12, v196
	v_ashrrev_i32_e32 v199, 31, v198
	v_lshlrev_b64 v[198:199], 11, v[198:199]
	v_lshl_add_u64 v[198:199], v[162:163], 0, v[198:199]
	global_load_dwordx4 v[106:109], v[198:199], off
	v_add_u32_e32 v198, 14, v196
	v_ashrrev_i32_e32 v199, 31, v198
	v_lshlrev_b64 v[198:199], 11, v[198:199]
	v_lshl_add_u64 v[198:199], v[162:163], 0, v[198:199]
	global_load_dwordx4 v[94:97], v[198:199], off
	s_lshl_b64 s[86:87], s[84:85], 15
	v_lshl_add_u64 v[200:201], v[136:137], 0, s[86:87]
	s_lshl_b64 s[86:87], s[84:85], 10
	v_lshl_add_u64 v[202:203], v[138:139], 0, s[86:87]
	global_load_dwordx4 v[50:53], v[200:201], off
	global_load_dwordx4 v[46:49], v[200:201], off offset:1024
	global_load_dwordx4 v[42:45], v[200:201], off offset:2048
	global_load_dwordx4 v[38:41], v[200:201], off offset:3072
	global_load_dwordx4 v[66:69], v[202:203], off
	global_load_dwordx4 v[54:57], v[202:203], off offset:32
	global_load_dwordx4 v[58:61], v[202:203], off offset:64
	global_load_dwordx4 v[70:73], v[202:203], off offset:96
	s_cmp_eq_u32 s8, 0
	s_cbranch_scc1 .Lscan_first_B
	s_waitcnt vmcnt(20)
	s_branch .Lscan_go_B

; #define MFMA16(a, b, c) __builtin_amdgcn_mfma_f32_16x16x32_bf16((a), (b), (c), 0, 0, 0)
; DI void phase_scan(int wid0, const Params& p, unsigned char* lds, bool dry) {
;     ...
;             *(u32x4*)(vs + cur * 4608 + vj * 72 + vc8) = vnext;
;             LDS_BARRIER();
;             if (c + 1 < 65) vnext = *(const u32x4*)(vb + (size_t)((b * 64 + c) * 64 + vj) * 2048 + colv + vc8);
;             const unsigned vao = vs_base + (unsigned)(cur * 9216 + (8 * l4 + (l15 >> 2)) * 144 + 2 * (16 * cb0 + 4 * (l15 & 3)));
;             const unsigned vau = vs_base + (unsigned)(cur * 9216 + (8 * hi + (l15 >> 2)) * 144 + 2 * (16 * ((lane >> 4) & 1) + 4 * (l15 & 3)));
;             s16x4 ol[2][2], oh[2][2], ul0[4], uh0[4], ul1[4], uh1[4];
; #pragma unroll
;             for (int cc = 0; cc < 2; ++cc)
; #pragma unroll
;                 for (int s = 0; s < 2; ++s) { ol[cc][s] = tr_read0(vao + cc * 32 + s * 32 * 144); oh[cc][s] = tr_read0(vao + cc * 32 + s * 32 * 144 + 4 * 144); }
; #pragma unroll
;             for (int s = 0; s < 2; ++s) {
;                 ul0[s] = tr_read0(vau + s * 16 * 144); uh0[s] = tr_read0(vau + s * 16 * 144 + 4 * 144);
;                 ul1[s] = tr_read0(vau + s * 16 * 144 + 64); uh1[s] = tr_read0(vau + s * 16 * 144 + 4 * 144 + 64);
;             }
;             {
;                 __builtin_amdgcn_sched_barrier(0);
;                 f32x4 oacc[2];
; #pragma unroll
;                 for (int cc = 0; cc < 2; ++cc) {
;                     const int cb = cb0 + cc; oacc[cc] = (f32x4){0.f, 0.f, 0.f, 0.f};
; #pragma unroll
;                     for (int s = 0; s < 2; ++s) oacc[cc] = MFMA16(PK8(ol[cc][s], oh[cc][s]), at[s], oacc[cc]);
;                     const bf16_t* sp = sbt + cur * 16896 + (16 * cb + l15) * 264 + 8 * l4;
; #pragma unroll
;                     for (int s = 0; s < 8; ++s) { const bf16x8 bfr = *(const bf16x8*)(sp + 32 * s); oacc[cc] = MFMA16(bfr, aq[s], oacc[cc]); }
;                 }
; #pragma unroll
;                 for (int s = 2; s < 4; ++s) {
;                     ul0[s] = tr_read0(vau + s * 16 * 144); uh0[s] = tr_read0(vau + s * 16 * 144 + 4 * 144);
;                     ul1[s] = tr_read0(vau + s * 16 * 144 + 64); uh1[s] = tr_read0(vau + s * 16 * 144 + 4 * 144 + 64);
;                 }
; #pragma unroll
;                 for (int cc = 0; cc < 2; ++cc) {
;                     const int col = colv + 16 * (cb0 + cc) + 4 * l4;
.Lscan_body_B:
	v_add_u32_e32 v62, s9, v181
	v_add_u32_e32 v179, s9, v180
	ds_read_b64_tr_b16 v[198:199], v62 offset:576
	ds_read_b64_tr_b16 v[196:197], v62
	ds_read_b64_tr_b16 v[202:203], v62 offset:608
	ds_read_b64_tr_b16 v[200:201], v62 offset:32
	ds_read_b64_tr_b16 v[204:205], v62 offset:4608
	ds_read_b64_tr_b16 v[206:207], v62 offset:5184
	ds_read_b64_tr_b16 v[210:211], v62 offset:5216
	ds_read_b64_tr_b16 v[208:209], v62 offset:4640
	ds_read_b64_tr_b16 v[82:83], v179
	ds_read_b64_tr_b16 v[84:85], v179 offset:576
	ds_read_b64_tr_b16 v[80:81], v179 offset:640
	ds_read_b64_tr_b16 v[78:79], v179 offset:64
	ds_read_b64_tr_b16 v[74:75], v179 offset:2304
	ds_read_b64_tr_b16 v[76:77], v179 offset:2880
	ds_read_b64_tr_b16 v[64:65], v179 offset:2944
	ds_read_b64_tr_b16 v[62:63], v179 offset:2368
	s_waitcnt lgkmcnt(14)
	v_mfma_f32_16x16x32_bf16 v[196:199], v[196:199], v[214:217], 0
	s_mul_i32 s9, s7, 0x8400
	v_add_u32_e32 v212, s9, v182
	v_add_u32_e32 v213, v212, v145
	s_waitcnt lgkmcnt(12)
	v_mfma_f32_16x16x32_bf16 v[214:217], v[200:203], v[214:217], 0
	v_add_u32_e32 v200, v212, v189
	v_pk_mul_f32 v[32:33], v[32:33], v[234:235]
	v_pk_mul_f32 v[28:29], v[28:29], v[186:187]
	s_waitcnt lgkmcnt(10)
	v_mfma_f32_16x16x32_bf16 v[196:199], v[204:207], v[218:221], v[196:199]
	ds_read_b128 v[204:207], v213
	v_pk_mul_f32 v[24:25], v[24:25], v[174:175]
	v_pk_mul_f32 v[20:21], v[20:21], v[170:171]
	s_waitcnt lgkmcnt(9)
	v_mfma_f32_16x16x32_bf16 v[214:217], v[208:211], v[218:221], v[214:217]
	ds_read_b128 v[218:221], v200
	v_pk_mul_f32 v[18:19], v[18:19], v[168:169]
	v_pk_mul_f32 v[30:31], v[30:31], v[232:233]
	s_waitcnt lgkmcnt(1)
	v_mfma_f32_16x16x32_bf16 v[196:199], v[204:207], v[222:225], v[196:199]
	ds_read_b128 v[204:207], v213 offset:64
	v_pk_mul_f32 v[26:27], v[26:27], v[184:185]
	v_pk_mul_f32 v[22:23], v[22:23], v[172:173]
	s_waitcnt lgkmcnt(1)
	v_mfma_f32_16x16x32_bf16 v[222:225], v[218:221], v[222:225], v[214:217]
	v_mul_f32_e64 v16, v16, v234
	v_mul_f32_e64 v17, v17, v235
	v_pk_mul_f32 v[12:13], v[12:13], v[186:187]
	v_pk_mul_f32 v[8:9], v[8:9], v[174:175]
	ds_read_b128 v[214:217], v200 offset:64
	s_waitcnt lgkmcnt(1)
	v_mfma_f32_16x16x32_bf16 v[196:199], v[204:207], v[226:229], v[196:199]
	ds_read_b128 v[204:207], v213 offset:128
	v_pk_mul_f32 v[4:5], v[4:5], v[170:171]
	v_pk_mul_f32 v[2:3], v[2:3], v[168:169]
	s_waitcnt lgkmcnt(1)
	v_mfma_f32_16x16x32_bf16 v[226:229], v[214:217], v[226:229], v[222:225]
	s_nop 2
	ds_read_b128 v[222:225], v200 offset:128
	v_pk_mul_f32 v[14:15], v[14:15], v[232:233]
	v_pk_mul_f32 v[10:11], v[10:11], v[184:185]
	s_waitcnt lgkmcnt(1)
	v_mfma_f32_16x16x32_bf16 v[196:199], v[204:207], v[236:239], v[196:199]
	ds_read_b128 v[204:207], v213 offset:192
	v_pk_mul_f32 v[6:7], v[6:7], v[172:173]
	s_waitcnt lgkmcnt(1)
	v_mfma_f32_16x16x32_bf16 v[226:229], v[222:225], v[236:239], v[226:229]
	ds_read_b128 v[236:239], v200 offset:192
	s_waitcnt lgkmcnt(1)
	v_mfma_f32_16x16x32_bf16 v[196:199], v[204:207], v[240:243], v[196:199]
	ds_read_b128 v[204:207], v213 offset:256
	s_waitcnt lgkmcnt(1)
	v_mfma_f32_16x16x32_bf16 v[240:243], v[236:239], v[240:243], v[226:229]
	s_nop 2
	ds_read_b128 v[226:229], v200 offset:256
	s_waitcnt lgkmcnt(1)
	v_mfma_f32_16x16x32_bf16 v[196:199], v[204:207], v[248:251], v[196:199]
	ds_read_b128 v[204:207], v213 offset:320
	s_waitcnt lgkmcnt(1)
	v_mfma_f32_16x16x32_bf16 v[240:243], v[226:229], v[248:251], v[240:243]
	ds_read_b128 v[226:229], v200 offset:320
	s_waitcnt lgkmcnt(1)
	v_mfma_f32_16x16x32_bf16 v[196:199], v[204:207], v[252:255], v[196:199]
	ds_read_b128 v[204:207], v213 offset:384
	s_waitcnt lgkmcnt(1)
	v_mfma_f32_16x16x32_bf16 v[240:243], v[226:229], v[252:255], v[240:243]
	ds_read_b128 v[252:255], v200 offset:384
	s_waitcnt lgkmcnt(1)
	v_mfma_f32_16x16x32_bf16 v[196:199], v[204:207], v[140:143], v[196:199]
	ds_read_b128 v[204:207], v213 offset:448
	s_waitcnt lgkmcnt(1)
	v_mfma_f32_16x16x32_bf16 v[240:243], v[252:255], v[140:143], v[240:243]
	ds_read_b128 v[252:255], v200 offset:448
	v_add_u32_e32 v140, s8, v194
	v_ashrrev_i32_e32 v141, 31, v140
	s_waitcnt lgkmcnt(1)
	v_mfma_f32_16x16x32_bf16 v[196:199], v[204:207], v[146:149], v[196:199]
	v_lshlrev_b64 v[140:141], 12, v[140:141]
	v_lshl_add_u64 v[140:141], s[28:29], 0, v[140:141]
	v_lshl_add_u64 v[236:237], v[140:141], 0, v[0:1]
	s_waitcnt lgkmcnt(0)
	v_mfma_f32_16x16x32_bf16 v[240:243], v[252:255], v[146:149], v[240:243]
	ds_read_b64_tr_b16 v[252:253], v179 offset:4608
	ds_read_b64_tr_b16 v[254:255], v179 offset:5184
	ds_read_b64_tr_b16 v[146:147], v179 offset:4672
	ds_read_b64_tr_b16 v[148:149], v179 offset:5248
	ds_read_b64_tr_b16 v[226:227], v179 offset:6912
	ds_read_b64_tr_b16 v[228:229], v179 offset:7488
	ds_read_b64_tr_b16 v[248:249], v179 offset:6976
	ds_read_b64_tr_b16 v[250:251], v179 offset:7552
	v_mov_b32_e32 v179, v1
	v_cvt_pk_bf16_f32 v142, v196, v197
	v_cvt_pk_bf16_f32 v143, v198, v199
	v_cvt_pk_bf16_f32 v240, v240, v241
	v_cvt_pk_bf16_f32 v241, v242, v243
	v_lshl_add_u64 v[242:243], v[140:141], 0, v[178:179]
	global_store_dwordx2 v[236:237], v[142:143], off
	global_store_dwordx2 v[242:243], v[240:241], off
	v_mfma_f32_32x32x16_bf16 v[18:33], v[150:153], v[82:85], v[18:33]
	s_xor_b32 s7, s7, 1
	s_mul_i32 s7, s7, 0x8400
	s_add_i32 s8, s8, 64
	s_add_i32 s6, s6, 4
	s_add_i32 s2, s2, 1
	s_cmpk_eq_i32 s8, 0x1000
	v_mfma_f32_32x32x16_bf16 v[2:17], v[150:153], v[78:81], v[2:17]
	v_mfma_f32_32x32x16_bf16 v[18:33], v[154:157], v[74:77], v[18:33]
	v_mfma_f32_32x32x16_bf16 v[2:17], v[154:157], v[62:65], v[2:17]
	v_add_u32_e32 v154, s7, v131
	v_add_u32_e32 v155, 0x4000, v154
	s_waitcnt lgkmcnt(6)
	v_mfma_f32_32x32x16_bf16 v[18:33], v[158:161], v[252:255], v[18:33]
	s_waitcnt lgkmcnt(4)
	v_mfma_f32_32x32x16_bf16 v[2:17], v[158:161], v[146:149], v[2:17]
	s_waitcnt lgkmcnt(2)
	v_mfma_f32_32x32x16_bf16 v[18:33], v[164:167], v[226:229], v[18:33]
	s_waitcnt lgkmcnt(0)
	v_mfma_f32_32x32x16_bf16 v[2:17], v[164:167], v[248:251], v[2:17]
	s_nop 9
	v_cvt_pk_bf16_f32 v158, v18, v19
	v_cvt_pk_bf16_f32 v159, v20, v21
	v_cvt_pk_bf16_f32 v166, v22, v23
	v_cvt_pk_bf16_f32 v167, v24, v25
	ds_write2_b64 v154, v[158:159], v[166:167] offset1:2
	v_cvt_pk_bf16_f32 v158, v30, v31
	v_cvt_pk_bf16_f32 v159, v32, v33
	v_cvt_pk_bf16_f32 v164, v2, v3
	v_cvt_pk_bf16_f32 v165, v4, v5
	v_cvt_pk_bf16_f32 v160, v6, v7
	v_cvt_pk_bf16_f32 v161, v8, v9
	ds_write2_b64 v155, v[164:165], v[160:161] offset0:64 offset1:66
	v_cvt_pk_bf16_f32 v164, v26, v27
	v_cvt_pk_bf16_f32 v165, v28, v29
	v_cvt_pk_bf16_f32 v166, v10, v11
	v_cvt_pk_bf16_f32 v167, v12, v13
	v_cvt_pk_bf16_f32 v160, v14, v15
	v_cvt_pk_bf16_f32 v161, v16, v17
	ds_write2_b64 v154, v[164:165], v[158:159] offset0:4 offset1:6
	ds_write2_b64 v155, v[166:167], v[160:161] offset0:68 offset1:70
	s_cbranch_scc1 .LBB0_228
	s_branch .Lscan_top_A
